# Fm DFT table: one sincospif per (s,t) now feeds 4 rows (cos/sin rows s and s+1024 via the (-1)^t symmetry), on top of K-split + QK fusion
# speedup vs baseline: 1.0033x; 1.0007x over previous
; __device__ __forceinline__ u32x4 pack8(const f32x4 a, const f32x4 b) { u32x4 w; w.x = cvt_pk_bf16(a[0], a[1]); w.y = cvt_pk_bf16(a[2], a[3]); w.z = cvt_pk_bf16(b[0], b[1]); w.w = cvt_pk_bf16(b[2], b[3]); return w; }
; __device__ void ph_prep(const Params& p, LAS unsigned char* lds_in, const int WID) {
;     ...
;     bf16_t* Fm = (bf16_t*)(p.ws + OFF_FM);
;     for (int it = blockIdx.x * NTHREADS + tid; it < 4096 * 256; it += gridDim.x * NTHREADS) {
;         const int row = it >> 8, t0 = (it & 255) * 8, s = row & 2047, part = row >> 11;
;         f32x4 a, b;
; #pragma unroll
;         for (int j = 0; j < 8; ++j) { float sn, cs; sincospif((float)((s * (t0 + j)) & 2047) / 1024.0f, &sn, &cs); const float v = (part ? sn : cs) * 0.022097086912079608f; if (j < 4) a[j] = v; else b[j - 4] = v; }
;         *(u32x4*)(Fm + (size_t)row * 2048 + t0) = pack8(a, b);
;     }
.LBB0_110:
	s_add_u32 s76, s92, 0xf800000
	s_addc_u32 s77, s93, 0
	s_lshl_b32 s84, s90, 9
	v_add_u32_e32 v8, s84, v50
	s_mov_b32 s0, 0x100000
	v_cmp_gt_i32_e32 vcc, s0, v8
	s_and_saveexec_b64 s[16:17], vcc
	s_cbranch_execz .LBB0_113
	v_lshlrev_b32_e32 v2, 3, v50
	s_lshl_b32 s21, s91, 9
	v_lshl_add_u32 v9, s90, 12, v2
	s_lshl_b32 s22, s91, 12
	s_mov_b64 s[18:19], 0
	s_mov_b32 s23, 0x80000
	s_mov_b32 s20, 0x3a800000
	s_mov_b32 s25, 0x7f800000
	v_mov_b32_e32 v10, 0x3e642e9d
	v_mov_b32_e32 v11, 0xbf1f24be
	s_brev_b32 s26, 1
	v_mov_b32_e32 v12, 0x7fc00000
	v_mov_b32_e32 v3, 0
	s_mov_b32 s27, 0x3ffff
.LBB0_112:
	v_ashrrev_i32_e32 v4, 8, v8
	v_or_b32_e32 v2, 2, v9
	v_or_b32_e32 v5, 3, v9
	v_or_b32_e32 v6, 4, v9
	v_or_b32_e32 v7, 5, v9
	v_or_b32_e32 v13, 6, v9
	v_or_b32_e32 v14, 7, v9
	v_and_b32_e32 v15, 0x7f8, v9
	v_mul_lo_u32 v16, v9, v4
	v_mul_lo_u32 v17, v2, v4
	v_mul_lo_u32 v18, v5, v4
	v_mul_lo_u32 v6, v6, v4
	v_mul_lo_u32 v7, v7, v4
	v_mul_lo_u32 v13, v13, v4
	v_mul_lo_u32 v14, v14, v4
	v_lshlrev_b32_e32 v2, 1, v15
	v_add_u32_e32 v15, v16, v4
	v_and_b32_e32 v17, 0x7fe, v17
	v_and_b32_e32 v18, 0x7ff, v18
	v_and_b32_e32 v16, 0x7f8, v16
	v_and_b32_e32 v6, 0x7fc, v6
	v_and_b32_e32 v19, 0x7ff, v7
	v_and_b32_e32 v13, 0x7fe, v13
	v_and_b32_e32 v20, 0x7ff, v14
	v_and_b32_e32 v21, 0x7ff, v15
	v_cvt_f32_u32_e32 v15, v17
	v_cvt_f32_u32_e32 v14, v18
	v_cvt_f32_u32_e32 v7, v16
	v_cvt_f32_u32_e32 v17, v6
	v_cvt_f32_u32_e32 v16, v19
	v_cvt_f32_u32_e32 v19, v13
	v_cvt_f32_u32_e32 v18, v20
	v_cvt_f32_u32_e32 v6, v21
	v_ashrrev_i32_e32 v5, 31, v4
	v_lshlrev_b64 v[4:5], 12, v[4:5]
	v_pk_mul_f32 v[14:15], v[14:15], s[20:21] op_sel_hi:[1,0]
	v_lshl_add_u64 v[4:5], s[76:77], 0, v[4:5]
	v_pk_mul_f32 v[16:17], v[16:17], s[20:21] op_sel_hi:[1,0]
	v_pk_mul_f32 v[18:19], v[18:19], s[20:21] op_sel_hi:[1,0]
	v_pk_mul_f32 v[6:7], v[6:7], s[20:21] op_sel_hi:[1,0]
	v_pk_mul_f32 v[20:21], v[14:15], 0.5 op_sel_hi:[1,0]
	v_lshl_add_u64 v[4:5], v[4:5], 0, v[2:3]
	v_pk_mul_f32 v[22:23], v[16:17], 0.5 op_sel_hi:[1,0]
	v_pk_mul_f32 v[24:25], v[18:19], 0.5 op_sel_hi:[1,0]
	v_pk_mul_f32 v[26:27], v[6:7], 0.5 op_sel_hi:[1,0]
	v_fract_f32_e32 v2, v21
	v_fract_f32_e32 v13, v20
	v_fract_f32_e32 v28, v23
	v_fract_f32_e32 v29, v22
	v_fract_f32_e32 v30, v25
	v_fract_f32_e32 v31, v24
	v_fract_f32_e32 v32, v27
	v_fract_f32_e32 v33, v26
	v_add_f32_e32 v2, v2, v2
	v_cmp_neq_f32_e32 vcc, s25, v21
	v_add_f32_e32 v13, v13, v13
	v_cmp_neq_f32_e64 s[0:1], s25, v20
	v_add_f32_e32 v20, v28, v28
	v_cmp_neq_f32_e64 s[4:5], s25, v23
	v_add_f32_e32 v21, v29, v29
	v_cmp_neq_f32_e64 s[6:7], s25, v22
	v_add_f32_e32 v22, v30, v30
	v_cmp_neq_f32_e64 s[8:9], s25, v25
	v_add_f32_e32 v23, v31, v31
	v_cmp_neq_f32_e64 s[10:11], s25, v24
	v_add_f32_e32 v24, v32, v32
	v_add_f32_e32 v25, v33, v33
	v_cmp_neq_f32_e64 s[12:13], s25, v26
	v_cndmask_b32_e32 v2, 0, v2, vcc
	v_cmp_lt_f32_e32 vcc, 1.0, v15
	v_cmp_neq_f32_e64 s[14:15], s25, v27
	v_cndmask_b32_e64 v13, 0, v13, s[0:1]
	v_cmp_lt_f32_e64 s[0:1], 1.0, v14
	v_cndmask_b32_e64 v20, 0, v20, s[4:5]
	v_cmp_lt_f32_e64 s[4:5], 1.0, v17
	v_cndmask_b32_e64 v21, 0, v21, s[6:7]
	v_cmp_lt_f32_e64 s[6:7], 1.0, v16
	v_cndmask_b32_e64 v22, 0, v22, s[8:9]
	v_cmp_lt_f32_e64 s[8:9], 1.0, v19
	v_cndmask_b32_e64 v23, 0, v23, s[10:11]
	v_cmp_lt_f32_e64 s[10:11], 1.0, v18
	v_cndmask_b32_e64 v24, 0, v24, s[14:15]
	v_cndmask_b32_e64 v25, 0, v25, s[12:13]
	v_cmp_lt_f32_e64 s[12:13], 1.0, v6
	v_cndmask_b32_e32 v2, v15, v2, vcc
	v_cmp_lt_f32_e32 vcc, 1.0, v7
	v_cndmask_b32_e64 v13, v14, v13, s[0:1]
	v_cndmask_b32_e64 v20, v17, v20, s[4:5]
	v_cndmask_b32_e64 v21, v16, v21, s[6:7]
	v_cndmask_b32_e64 v22, v19, v22, s[8:9]
	v_cndmask_b32_e64 v23, v18, v23, s[10:11]
	v_cndmask_b32_e32 v24, v7, v24, vcc
	v_cndmask_b32_e64 v25, v6, v25, s[12:13]
	v_add_f32_e32 v26, v2, v2
	v_add_f32_e32 v27, v13, v13
	v_add_f32_e32 v28, v20, v20
	v_add_f32_e32 v29, v21, v21
	v_add_f32_e32 v30, v22, v22
	v_add_f32_e32 v31, v23, v23
	v_add_f32_e32 v32, v24, v24
	v_add_f32_e32 v33, v25, v25
	v_rndne_f32_e32 v26, v26
	v_rndne_f32_e32 v27, v27
	v_rndne_f32_e32 v28, v28
	v_rndne_f32_e32 v29, v29
	v_rndne_f32_e32 v30, v30
	v_rndne_f32_e32 v31, v31
	v_rndne_f32_e32 v32, v32
	v_rndne_f32_e32 v33, v33
	v_fmac_f32_e32 v2, -0.5, v26
	v_cvt_i32_f32_e32 v34, v26
	v_cvt_i32_f32_e32 v26, v27
	v_fmac_f32_e32 v13, -0.5, v27
	v_cvt_i32_f32_e32 v27, v28
	v_fmac_f32_e32 v20, -0.5, v28
	v_cvt_i32_f32_e32 v28, v29
	v_fmac_f32_e32 v21, -0.5, v29
	v_cvt_i32_f32_e32 v29, v30
	v_fmac_f32_e32 v22, -0.5, v30
	v_cvt_i32_f32_e32 v30, v31
	v_fmac_f32_e32 v23, -0.5, v31
	v_cvt_i32_f32_e32 v31, v32
	v_fmac_f32_e32 v24, -0.5, v32
	v_cvt_i32_f32_e32 v32, v33
	v_fmac_f32_e32 v25, -0.5, v33
	v_mul_f32_e32 v33, v2, v2
	v_mul_f32_e32 v35, v13, v13
	v_mul_f32_e32 v36, v20, v20
	v_mul_f32_e32 v37, v21, v21
	v_mul_f32_e32 v38, v22, v22
	v_mul_f32_e32 v39, v23, v23
	v_mul_f32_e32 v40, v24, v24
	v_mul_f32_e32 v41, v25, v25
	v_fmamk_f32 v44, v33, 0x3e75aa41, v11
	v_fmamk_f32 v42, v33, 0x3d4be544, v10
	v_fmamk_f32 v45, v35, 0x3d4be544, v10
	v_fmamk_f32 v47, v35, 0x3e75aa41, v11
	v_fmamk_f32 v48, v36, 0x3d4be544, v10
	v_fmamk_f32 v50, v36, 0x3e75aa41, v11
	v_fmamk_f32 v51, v37, 0x3d4be544, v10
	v_fmamk_f32 v53, v37, 0x3e75aa41, v11
	v_fmamk_f32 v56, v38, 0x3e75aa41, v11
	v_fmamk_f32 v57, v39, 0x3d4be544, v10
	v_fmamk_f32 v59, v39, 0x3e75aa41, v11
	v_fmamk_f32 v62, v40, 0x3e75aa41, v11
	v_fmamk_f32 v65, v41, 0x3e75aa41, v11
	v_fmaak_f32 v44, v33, v44, 0x40234736
	v_mul_f32_e32 v43, v2, v33
	v_fmamk_f32 v54, v38, 0x3d4be544, v10
	v_fmamk_f32 v60, v40, 0x3d4be544, v10
	v_fmamk_f32 v63, v41, 0x3d4be544, v10
	v_fmaak_f32 v42, v33, v42, 0xbfaad1da
; __device__ void ph_prep(const Params& p, LAS unsigned char* lds_in, const int WID) {
;     ...
;         for (int j = 0; j < 8; ++j) { float sn, cs; sincospif((float)((s * (t0 + j)) & 2047) / 1024.0f, &sn, &cs); const float v = (part ? sn : cs) * 0.022097086912079608f; if (j < 4) a[j] = v; else b[j - 4] = v; }
	v_fmaak_f32 v45, v35, v45, 0xbfaad1da
	v_fmaak_f32 v47, v35, v47, 0x40234736
	v_fmaak_f32 v48, v36, v48, 0xbfaad1da
	v_fmaak_f32 v50, v36, v50, 0x40234736
	v_fmaak_f32 v51, v37, v51, 0xbfaad1da
	v_fmaak_f32 v53, v37, v53, 0x40234736
	v_fmaak_f32 v56, v38, v56, 0x40234736
	v_fmaak_f32 v57, v39, v57, 0xbfaad1da
	v_fmaak_f32 v59, v39, v59, 0x40234736
	v_fmaak_f32 v62, v40, v62, 0x40234736
	v_fmaak_f32 v65, v41, v65, 0x40234736
	v_fmaak_f32 v44, v33, v44, 0xc0a55e0e
	v_mul_f32_e32 v46, v13, v35
	v_mul_f32_e32 v49, v20, v36
	v_mul_f32_e32 v52, v21, v37
	v_mul_f32_e32 v55, v22, v38
	v_mul_f32_e32 v58, v23, v39
	v_mul_f32_e32 v61, v24, v40
	v_mul_f32_e32 v64, v25, v41
	v_fmaak_f32 v54, v38, v54, 0xbfaad1da
	v_fmaak_f32 v60, v40, v60, 0xbfaad1da
	v_fmaak_f32 v63, v41, v63, 0xbfaad1da
	v_fmaak_f32 v42, v33, v42, 0x4081e0d3
	v_fmaak_f32 v45, v35, v45, 0x4081e0d3
	v_fmaak_f32 v47, v35, v47, 0xc0a55e0e
	v_fmaak_f32 v48, v36, v48, 0x4081e0d3
	v_fmaak_f32 v50, v36, v50, 0xc0a55e0e
	v_fmaak_f32 v51, v37, v51, 0x4081e0d3
	v_fmaak_f32 v53, v37, v53, 0xc0a55e0e
	v_fmaak_f32 v56, v38, v56, 0xc0a55e0e
	v_fmaak_f32 v57, v39, v57, 0x4081e0d3
	v_fmaak_f32 v59, v39, v59, 0xc0a55e0e
	v_fmaak_f32 v62, v40, v62, 0xc0a55e0e
	v_fmaak_f32 v65, v41, v65, 0xc0a55e0e
	v_mul_f32_e32 v43, v43, v44
	v_and_b32_e32 v66, 1, v34
	v_fmaak_f32 v54, v38, v54, 0x4081e0d3
	v_fmaak_f32 v60, v40, v60, 0x4081e0d3
	v_fmaak_f32 v63, v41, v63, 0x4081e0d3
	v_fmaak_f32 v42, v33, v42, 0xc09de9e6
	v_fmaak_f32 v44, v35, v45, 0xc09de9e6
	v_mul_f32_e32 v45, v46, v47
	v_fmaak_f32 v46, v36, v48, 0xc09de9e6
	v_mul_f32_e32 v47, v49, v50
	v_fmaak_f32 v48, v37, v51, 0xc09de9e6
	v_mul_f32_e32 v49, v52, v53
	v_mul_f32_e32 v51, v55, v56
	v_fmaak_f32 v52, v39, v57, 0xc09de9e6
	v_mul_f32_e32 v53, v58, v59
	v_mul_f32_e32 v55, v61, v62
	v_mul_f32_e32 v57, v64, v65
	v_fmac_f32_e32 v43, 0x40490fdb, v2
	v_and_b32_e32 v67, 1, v26
	v_and_b32_e32 v68, 1, v27
	v_and_b32_e32 v69, 1, v28
	v_and_b32_e32 v70, 1, v29
	v_and_b32_e32 v71, 1, v30
	v_and_b32_e32 v72, 1, v31
	v_and_b32_e32 v73, 1, v32
	v_fmaak_f32 v50, v38, v54, 0xc09de9e6
	v_fmaak_f32 v54, v40, v60, 0xc09de9e6
	v_fmaak_f32 v56, v41, v63, 0xc09de9e6
	v_fma_f32 v33, v33, v42, 1.0
	v_fmac_f32_e32 v45, 0x40490fdb, v13
	v_fmac_f32_e32 v47, 0x40490fdb, v20
	v_fmac_f32_e32 v49, 0x40490fdb, v21
	v_fmac_f32_e32 v51, 0x40490fdb, v22
	v_fmac_f32_e32 v53, 0x40490fdb, v23
	v_fmac_f32_e32 v55, 0x40490fdb, v24
	v_fmac_f32_e32 v57, 0x40490fdb, v25
	v_xor_b32_e32 v25, 0x80000000, v43
	v_cmp_eq_u32_e32 vcc, 0, v66
	v_lshlrev_b32_e32 v34, 30, v34
	v_fma_f32 v2, v35, v44, 1.0
	v_fma_f32 v13, v36, v46, 1.0
	v_fma_f32 v20, v37, v48, 1.0
	v_fma_f32 v21, v38, v50, 1.0
	v_fma_f32 v22, v39, v52, 1.0
	v_fma_f32 v23, v40, v54, 1.0
	v_fma_f32 v24, v41, v56, 1.0
	v_xor_b32_e32 v35, 0x80000000, v45
	v_cmp_eq_u32_e64 s[0:1], 0, v67
	v_xor_b32_e32 v36, 0x80000000, v47
	v_cmp_eq_u32_e64 s[4:5], 0, v68
	v_xor_b32_e32 v37, 0x80000000, v49
	v_cmp_eq_u32_e64 s[6:7], 0, v69
	v_xor_b32_e32 v38, 0x80000000, v51
	v_cmp_eq_u32_e64 s[8:9], 0, v70
	v_xor_b32_e32 v39, 0x80000000, v53
	v_cmp_eq_u32_e64 s[10:11], 0, v71
	v_xor_b32_e32 v40, 0x80000000, v55
	v_xor_b32_e32 v41, 0x80000000, v57
	v_cmp_eq_u32_e64 s[12:13], 0, v73
	v_cndmask_b32_e32 v25, v25, v33, vcc
	v_cndmask_b32_e32 v33, v33, v43, vcc
	v_cmp_eq_u32_e32 vcc, 0, v72
	v_lshlrev_b32_e32 v26, 30, v26
	v_lshlrev_b32_e32 v27, 30, v27
	v_lshlrev_b32_e32 v28, 30, v28
	v_lshlrev_b32_e32 v29, 30, v29
	v_lshlrev_b32_e32 v30, 30, v30
	v_lshlrev_b32_e32 v31, 30, v31
	v_lshlrev_b32_e32 v32, 30, v32
	v_cndmask_b32_e64 v35, v35, v2, s[0:1]
	v_cndmask_b32_e64 v2, v2, v45, s[0:1]
	v_cndmask_b32_e64 v36, v36, v13, s[4:5]
	v_cndmask_b32_e64 v13, v13, v47, s[4:5]
	v_cndmask_b32_e64 v37, v37, v20, s[6:7]
; __device__ __forceinline__ u32x4 pack8(const f32x4 a, const f32x4 b) { u32x4 w; w.x = cvt_pk_bf16(a[0], a[1]); w.y = cvt_pk_bf16(a[2], a[3]); w.z = cvt_pk_bf16(b[0], b[1]); w.w = cvt_pk_bf16(b[2], b[3]); return w; }
; __device__ void ph_prep(const Params& p, LAS unsigned char* lds_in, const int WID) {
;     ...
;         for (int j = 0; j < 8; ++j) { float sn, cs; sincospif((float)((s * (t0 + j)) & 2047) / 1024.0f, &sn, &cs); const float v = (part ? sn : cs) * 0.022097086912079608f; if (j < 4) a[j] = v; else b[j - 4] = v; }
;         *(u32x4*)(Fm + (size_t)row * 2048 + t0) = pack8(a, b);
	v_cndmask_b32_e64 v20, v20, v49, s[6:7]
	v_cndmask_b32_e64 v38, v38, v21, s[8:9]
	v_cndmask_b32_e64 v21, v21, v51, s[8:9]
	v_cndmask_b32_e64 v39, v39, v22, s[10:11]
	v_cndmask_b32_e64 v22, v22, v53, s[10:11]
	v_cndmask_b32_e32 v40, v40, v23, vcc
	v_cndmask_b32_e32 v23, v23, v55, vcc
	v_cndmask_b32_e64 v41, v41, v24, s[12:13]
	v_cndmask_b32_e64 v24, v24, v57, s[12:13]
	v_bitop3_b32 v25, v25, v34, s26 bitop3:0x78
	v_cmp_lg_f32_e32 vcc, s25, v15
	v_bitop3_b32 v15, v33, v34, s26 bitop3:0x78
	v_bitop3_b32 v33, v35, v26, s26 bitop3:0x78
	v_cmp_lg_f32_e64 s[0:1], s25, v14
	v_bitop3_b32 v2, v2, v26, s26 bitop3:0x78
	v_bitop3_b32 v14, v36, v27, s26 bitop3:0x78
	v_cmp_lg_f32_e64 s[4:5], s25, v17
	v_bitop3_b32 v13, v13, v27, s26 bitop3:0x78
	v_bitop3_b32 v17, v37, v28, s26 bitop3:0x78
	v_cmp_lg_f32_e64 s[6:7], s25, v16
	v_bitop3_b32 v16, v20, v28, s26 bitop3:0x78
	v_bitop3_b32 v20, v38, v29, s26 bitop3:0x78
	v_cmp_lg_f32_e64 s[8:9], s25, v19
	v_bitop3_b32 v19, v21, v29, s26 bitop3:0x78
	v_bitop3_b32 v21, v39, v30, s26 bitop3:0x78
	v_cmp_lg_f32_e64 s[10:11], s25, v18
	v_bitop3_b32 v18, v22, v30, s26 bitop3:0x78
	v_bitop3_b32 v22, v40, v31, s26 bitop3:0x78
	v_bitop3_b32 v23, v23, v31, s26 bitop3:0x78
	v_bitop3_b32 v26, v41, v32, s26 bitop3:0x78
	v_cmp_lg_f32_e64 s[12:13], s25, v6
	v_bitop3_b32 v6, v24, v32, s26 bitop3:0x78
	v_cndmask_b32_e32 v24, v12, v25, vcc
	v_cndmask_b32_e32 v15, v12, v15, vcc
	v_cmp_lg_f32_e32 vcc, s25, v7
	v_cndmask_b32_e64 v25, v12, v33, s[0:1]
	v_cndmask_b32_e64 v2, v12, v2, s[0:1]
	v_cndmask_b32_e64 v14, v12, v14, s[4:5]
	v_cndmask_b32_e64 v13, v12, v13, s[4:5]
	v_cndmask_b32_e64 v17, v12, v17, s[6:7]
	v_cndmask_b32_e64 v16, v12, v16, s[6:7]
	v_cndmask_b32_e64 v20, v12, v20, s[8:9]
	v_cndmask_b32_e64 v19, v12, v19, s[8:9]
	v_cndmask_b32_e64 v21, v12, v21, s[10:11]
	v_cndmask_b32_e64 v18, v12, v18, s[10:11]
	v_cndmask_b32_e32 v7, v12, v22, vcc
	v_cndmask_b32_e32 v22, v12, v23, vcc
	v_cndmask_b32_e64 v23, v12, v26, s[12:13]
	v_cndmask_b32_e64 v6, v12, v6, s[12:13]
	v_add_u32_e32 v8, s21, v8
	v_cmp_lt_i32_e32 vcc, s27, v8
	v_add_u32_e32 v9, s22, v9
	s_or_b64 s[18:19], vcc, s[18:19]
	v_mul_f32_e32 v7, 0x3cb504f3, v7
	v_mul_f32_e32 v23, 0x3cb504f3, v23
	v_mul_f32_e32 v24, 0x3cb504f3, v24
	v_mul_f32_e32 v25, 0x3cb504f3, v25
	v_mul_f32_e32 v14, 0x3cb504f3, v14
	v_mul_f32_e32 v17, 0x3cb504f3, v17
	v_mul_f32_e32 v20, 0x3cb504f3, v20
	v_mul_f32_e32 v21, 0x3cb504f3, v21
	v_mul_f32_e32 v22, 0x3cb504f3, v22
	v_mul_f32_e32 v6, 0x3cb504f3, v6
	v_mul_f32_e32 v15, 0x3cb504f3, v15
	v_mul_f32_e32 v2, 0x3cb504f3, v2
	v_mul_f32_e32 v13, 0x3cb504f3, v13
	v_mul_f32_e32 v16, 0x3cb504f3, v16
	v_mul_f32_e32 v19, 0x3cb504f3, v19
	v_mul_f32_e32 v18, 0x3cb504f3, v18
	v_cvt_pk_bf16_f32 v26, v7, v23
	v_cvt_pk_bf16_f32 v27, v24, v25
	v_cvt_pk_bf16_f32 v28, v14, v17
	v_cvt_pk_bf16_f32 v29, v20, v21
	v_cvt_pk_bf16_f32 v30, v22, v6
	v_cvt_pk_bf16_f32 v31, v15, v2
	v_cvt_pk_bf16_f32 v32, v13, v16
	v_cvt_pk_bf16_f32 v33, v19, v18
	v_add_co_u32_e32 v34, vcc, 0x800000, v4
	s_nop 0
	v_addc_co_u32_e32 v35, vcc, 0, v5, vcc
	v_add_co_u32_e32 v36, vcc, 0x400000, v4
	s_nop 0
	v_addc_co_u32_e32 v37, vcc, 0, v5, vcc
	v_add_co_u32_e32 v38, vcc, 0xc00000, v4
	s_nop 0
	v_addc_co_u32_e32 v39, vcc, 0, v5, vcc
	global_store_dwordx4 v[4:5], v[26:29], off
	global_store_dwordx4 v[34:35], v[30:33], off
	v_xor_b32_e32 v40, 0x80000000, v26
	v_xor_b32_e32 v41, 0x80000000, v27
	v_xor_b32_e32 v42, 0x80000000, v28
	v_xor_b32_e32 v43, 0x80000000, v29
	v_xor_b32_e32 v44, 0x80000000, v30
	v_xor_b32_e32 v45, 0x80000000, v31
	v_xor_b32_e32 v46, 0x80000000, v32
	v_xor_b32_e32 v47, 0x80000000, v33
	global_store_dwordx4 v[36:37], v[40:43], off
	global_store_dwordx4 v[38:39], v[44:47], off
	s_andn2_b64 exec, exec, s[18:19]
	s_cbranch_execnz .LBB0_112
